# in-projection tile loop: header waits only for the LDS-DMA prefetch (vmcnt 16), first-iteration sub-step 0/1 waits skipped, so result stores drain under the next K-loop; on top of flat barrier release
# baseline (speedup 1.0000x reference)
.LBB0_259:
	s_mov_b64 s[40:41], 0x80
	s_and_b32 s7, s4, 3
	s_add_i32 m0, s71, 0x18000
	v_lshl_add_u64 v[6:7], v[6:7], 0, s[40:41]
	s_lshl_b32 s75, s5, 6
	s_lshl_b32 s42, s5, 13
	s_lshl_b32 s43, s7, 12
	s_waitcnt vmcnt(2)
	s_barrier
	global_load_lds_dwordx4 v[6:7], off
	v_lshl_add_u64 v[4:5], v[4:5], 0, s[40:41]
	s_add_i32 m0, s71, 0x1a000
	s_add_i32 s76, s71, 0x8000
	s_add_i32 s77, s71, 0xa000
	global_load_lds_dwordx4 v[4:5], off
	v_lshl_add_u64 v[0:1], v[0:1], 0, s[40:41]
	s_mov_b32 m0, s76
	s_add_u32 s4, s64, 0x80080
	global_load_lds_dwordx4 v[0:1], off
	v_lshl_add_u64 v[0:1], v[2:3], 0, s[40:41]
	s_mov_b32 m0, s77
	s_addc_u32 s5, s65, 0
	global_load_lds_dwordx4 v[0:1], off
	s_add_i32 m0, s71, 0x1c000
	v_lshl_add_u64 v[0:1], s[4:5], 0, v[138:139]
	global_load_lds_dwordx4 v[0:1], off
	v_lshl_add_u64 v[0:1], s[4:5], 0, v[142:143]
	s_add_i32 m0, s71, 0x1e000
	v_and_b32_e32 v147, 15, v8
	global_load_lds_dwordx4 v[0:1], off
	v_bfe_u32 v0, v8, 4, 2
	v_lshlrev_b32_e32 v1, 4, v0
	v_lshlrev_b32_e32 v2, 2, v8
	v_lshlrev_b32_e32 v164, 3, v0
	v_lshl_or_b32 v1, v147, 6, v1
	v_and_b32_e32 v2, 32, v2
	s_cmpk_lt_u32 s6, 0x100
	v_bitop3_b32 v3, v1, s42, v2 bitop3:0xde
	v_bitop3_b32 v165, v1, s43, v2 bitop3:0xde
	s_cselect_b64 s[42:43], -1, 0
	v_lshl_or_b32 v146, s7, 5, v164
	s_bitcmp0_b32 s6, 6
	v_cmp_gt_u32_e64 s[6:7], 2, v0
	v_lshlrev_b32_e32 v0, 15, v9
	v_and_b32_e32 v0, 0xffff0000, v0
	v_lshl_add_u32 v0, v10, 12, v0
	v_and_b32_e32 v1, 1, v9
	v_lshl_or_b32 v0, v1, 6, v0
	v_lshl_add_u32 v148, v11, 1, v0
	v_lshlrev_b32_e32 v0, 15, v12
	v_and_b32_e32 v0, 0xffff0000, v0
	s_waitcnt vmcnt(6)
	v_lshl_add_u32 v0, v13, 12, v0
	v_and_b32_e32 v1, 1, v12
	s_cselect_b64 s[48:49], -1, 0
	v_lshl_or_b32 v0, v1, 6, v0
	s_add_i32 s85, 0, 0x10000
	s_add_i32 s86, 0, 0x14000
	s_ashr_i32 s81, s24, 31
	s_mov_b32 s82, s24
	s_ashr_i32 s83, s2, 31
	v_mov_b32_e32 v149, v145
	v_lshl_add_u32 v150, v14, 1, v0
	v_mov_b32_e32 v151, v145
	v_mov_b64_e32 v[152:153], 0x600
	v_mov_b64_e32 v[154:155], 0x5ff
	s_movk_i32 s84, 0xc1
	v_add_u32_e32 v166, s85, v165
	v_add_u32_e32 v167, s86, v165
	v_add_u32_e32 v168, 0, v3
	s_movk_i32 s87, 0x3000
	s_movk_i32 s88, 0x7cf0
	s_mov_b32 s89, 0x40000
	s_movk_i32 s90, 0x7df0
	s_movk_i32 s91, 0x7ef0
	s_movk_i32 s92, 0x7ff0
	v_mov_b32_e32 v169, 0x3e38aa3b
	v_mov_b32_e32 v170, 0x3e0293ee
	s_mov_b32 s93, 0
	s_barrier
	s_waitcnt vmcnt(0)
	s_branch .LBB0_262

.LBB0_264:
	s_ashr_i32 s55, s54, 31
	s_lshl_b64 s[56:57], s[54:55], 20
	s_add_u32 s56, s10, s56
	s_addc_u32 s57, s11, s57
	s_and_b64 s[58:59], s[4:5], exec
	s_cselect_b32 s55, s57, s63
	s_cselect_b32 s61, s56, s62
	s_ashr_i32 s51, s50, 31
	s_lshl_b64 s[58:59], s[50:51], 20
	s_add_u32 s58, s46, s58
	s_addc_u32 s59, s47, s59
	s_and_b64 s[66:67], s[4:5], exec
	s_cselect_b32 s51, s59, s65
	s_cselect_b32 s68, s58, s64
	s_add_u32 s62, s62, 0x80080
	s_addc_u32 s63, s63, 0
	s_add_u32 s69, s64, 0x100
	v_mov_b32_e32 v0, 0
	s_addc_u32 s94, s65, 0
	s_mov_b32 s95, -2
	v_mov_b32_e32 v1, v0
	v_mov_b32_e32 v2, v0
	v_mov_b32_e32 v3, v0
	v_mov_b32_e32 v4, v0
	v_mov_b32_e32 v5, v0
	v_mov_b32_e32 v6, v0
	v_mov_b32_e32 v7, v0
	s_waitcnt vmcnt(16)
	v_mov_b32_e32 v16, v0
	v_mov_b32_e32 v17, v0
	v_mov_b32_e32 v18, v0
	v_mov_b32_e32 v19, v0
	v_mov_b32_e32 v20, v0
	v_mov_b32_e32 v21, v0
	v_mov_b32_e32 v22, v0
	v_mov_b32_e32 v23, v0
	v_mov_b32_e32 v32, v0
	v_mov_b32_e32 v33, v0
	v_mov_b32_e32 v34, v0
	v_mov_b32_e32 v35, v0
	v_mov_b32_e32 v36, v0
	v_mov_b32_e32 v37, v0
	v_mov_b32_e32 v38, v0
	v_mov_b32_e32 v39, v0
	v_mov_b32_e32 v48, v0
	v_mov_b32_e32 v49, v0
	v_mov_b32_e32 v50, v0
	v_mov_b32_e32 v51, v0
	v_mov_b32_e32 v52, v0
	v_mov_b32_e32 v53, v0
	v_mov_b32_e32 v54, v0
	v_mov_b32_e32 v55, v0
	v_mov_b32_e32 v8, v0
	v_mov_b32_e32 v9, v0
	v_mov_b32_e32 v10, v0
	v_mov_b32_e32 v11, v0
	v_mov_b32_e32 v12, v0
	v_mov_b32_e32 v13, v0
	v_mov_b32_e32 v14, v0
	v_mov_b32_e32 v15, v0
	v_mov_b32_e32 v24, v0
	v_mov_b32_e32 v25, v0
	v_mov_b32_e32 v26, v0
	v_mov_b32_e32 v27, v0
	v_mov_b32_e32 v28, v0
	v_mov_b32_e32 v29, v0
	v_mov_b32_e32 v30, v0
	v_mov_b32_e32 v31, v0
	v_mov_b32_e32 v40, v0
	v_mov_b32_e32 v41, v0
	v_mov_b32_e32 v42, v0
	v_mov_b32_e32 v43, v0
	v_mov_b32_e32 v44, v0
	v_mov_b32_e32 v45, v0
	v_mov_b32_e32 v46, v0
	v_mov_b32_e32 v47, v0
	v_mov_b32_e32 v56, v0
	v_mov_b32_e32 v57, v0
	v_mov_b32_e32 v58, v0
	v_mov_b32_e32 v59, v0
	v_mov_b32_e32 v60, v0
	v_mov_b32_e32 v61, v0
	v_mov_b32_e32 v62, v0
	v_mov_b32_e32 v63, v0
	v_mov_b32_e32 v64, v0
	v_mov_b32_e32 v65, v0
	v_mov_b32_e32 v66, v0
	v_mov_b32_e32 v67, v0
	v_mov_b32_e32 v68, v0
	v_mov_b32_e32 v69, v0
	v_mov_b32_e32 v70, v0
	v_mov_b32_e32 v71, v0
	v_mov_b32_e32 v80, v0
	v_mov_b32_e32 v81, v0
	v_mov_b32_e32 v82, v0
	v_mov_b32_e32 v83, v0
	v_mov_b32_e32 v84, v0
	v_mov_b32_e32 v85, v0
	v_mov_b32_e32 v86, v0
	v_mov_b32_e32 v87, v0
	v_mov_b32_e32 v96, v0
	v_mov_b32_e32 v97, v0
	v_mov_b32_e32 v98, v0
	v_mov_b32_e32 v99, v0
	v_mov_b32_e32 v100, v0
	v_mov_b32_e32 v101, v0
	v_mov_b32_e32 v102, v0
	v_mov_b32_e32 v103, v0
	v_mov_b32_e32 v112, v0
	v_mov_b32_e32 v113, v0
	v_mov_b32_e32 v114, v0
	v_mov_b32_e32 v115, v0
	v_mov_b32_e32 v116, v0
	v_mov_b32_e32 v117, v0
	v_mov_b32_e32 v118, v0
	v_mov_b32_e32 v119, v0
	v_mov_b32_e32 v72, v0
	v_mov_b32_e32 v73, v0
	v_mov_b32_e32 v74, v0
	v_mov_b32_e32 v75, v0
	v_mov_b32_e32 v76, v0
	v_mov_b32_e32 v77, v0
	v_mov_b32_e32 v78, v0
	v_mov_b32_e32 v79, v0
	v_mov_b32_e32 v88, v0
	v_mov_b32_e32 v89, v0
	v_mov_b32_e32 v90, v0
	v_mov_b32_e32 v91, v0
	v_mov_b32_e32 v92, v0
	v_mov_b32_e32 v93, v0
	v_mov_b32_e32 v94, v0
	v_mov_b32_e32 v95, v0
	v_mov_b32_e32 v104, v0
	v_mov_b32_e32 v105, v0
	v_mov_b32_e32 v106, v0
	v_mov_b32_e32 v107, v0
	v_mov_b32_e32 v108, v0
	v_mov_b32_e32 v109, v0
	v_mov_b32_e32 v110, v0
	v_mov_b32_e32 v111, v0
	v_mov_b32_e32 v120, v0
	v_mov_b32_e32 v121, v0
	v_mov_b32_e32 v122, v0
	v_mov_b32_e32 v123, v0
	v_mov_b32_e32 v124, v0
	v_mov_b32_e32 v125, v0
	v_mov_b32_e32 v126, v0
	v_mov_b32_e32 v127, v0
	s_nop 0
	s_nop 0
	s_nop 0
	s_nop 0
	s_nop 0
	s_nop 0
	s_nop 0
	s_nop 0
	s_nop 0
	s_nop 0
	s_nop 0
	s_nop 0
	s_nop 0
	s_nop 0
.LBB0_265:
	ds_read_b128 v[128:131], v166
	ds_read_b128 v[132:135], v166 offset:1024
	ds_read_b128 v[156:159], v166 offset:2048
	ds_read_b128 v[160:163], v166 offset:3072
	ds_read_b128 v[172:175], v167
	ds_read_b128 v[176:179], v167 offset:1024
	ds_read_b128 v[180:183], v167 offset:2048
	ds_read_b128 v[184:187], v167 offset:3072
	s_add_u32 s64, s62, 0xfff80080
	s_addc_u32 s65, s63, -1
	s_cmp_eq_u32 s95, 28
	s_cselect_b32 s67, s55, s65
	s_cselect_b32 s66, s61, s64
	s_cselect_b32 s65, s51, s94
	s_cselect_b32 s64, s68, s69
	v_lshl_add_u64 v[220:221], s[62:63], 0, v[148:149]
	s_add_i32 m0, s71, 0xc000
	ds_read_b128 v[188:191], v168
	ds_read_b128 v[192:195], v168 offset:1024
	ds_read_b128 v[196:199], v168 offset:2048
	ds_read_b128 v[200:203], v168 offset:3072
	ds_read_b128 v[204:207], v168 offset:4096
	ds_read_b128 v[208:211], v168 offset:5120
	ds_read_b128 v[212:215], v168 offset:6144
	ds_read_b128 v[216:219], v168 offset:7168
	global_load_lds_dwordx4 v[220:221], off
	v_lshl_add_u64 v[220:221], s[62:63], 0, v[150:151]
	s_add_i32 m0, s71, 0xe000
	s_nop 0
	global_load_lds_dwordx4 v[220:221], off
	s_cmp_eq_u32 s95, -2
	s_cbranch_scc1 .Ltw0_0
	s_waitcnt vmcnt(8)
.Ltw0_0:
	s_waitcnt lgkmcnt(0)
	s_barrier
	s_setprio 1
	s_waitcnt lgkmcnt(0)
	v_mfma_f32_16x16x32_bf16 v[124:127], v[128:131], v[188:191], v[124:127]
	v_mfma_f32_16x16x32_bf16 v[120:123], v[156:159], v[188:191], v[120:123]
	v_mfma_f32_16x16x32_bf16 v[108:111], v[128:131], v[196:199], v[108:111]
	v_mfma_f32_16x16x32_bf16 v[104:107], v[156:159], v[196:199], v[104:107]
	v_mfma_f32_16x16x32_bf16 v[92:95], v[128:131], v[204:207], v[92:95]
	v_mfma_f32_16x16x32_bf16 v[88:91], v[156:159], v[204:207], v[88:91]
	v_mfma_f32_16x16x32_bf16 v[76:79], v[128:131], v[212:215], v[76:79]
	v_mfma_f32_16x16x32_bf16 v[72:75], v[156:159], v[212:215], v[72:75]
	v_mfma_f32_16x16x32_bf16 v[124:127], v[132:135], v[192:195], v[124:127]
	v_mfma_f32_16x16x32_bf16 v[120:123], v[160:163], v[192:195], v[120:123]
	v_mfma_f32_16x16x32_bf16 v[108:111], v[132:135], v[200:203], v[108:111]
	v_mfma_f32_16x16x32_bf16 v[104:107], v[160:163], v[200:203], v[104:107]
	v_mfma_f32_16x16x32_bf16 v[92:95], v[132:135], v[208:211], v[92:95]
	v_mfma_f32_16x16x32_bf16 v[88:91], v[160:163], v[208:211], v[88:91]
	v_mfma_f32_16x16x32_bf16 v[76:79], v[132:135], v[216:219], v[76:79]
	v_mfma_f32_16x16x32_bf16 v[72:75], v[160:163], v[216:219], v[72:75]
	s_setprio 0
	s_setprio 1
	v_mfma_f32_16x16x32_bf16 v[116:119], v[172:175], v[188:191], v[116:119]
	v_mfma_f32_16x16x32_bf16 v[112:115], v[180:183], v[188:191], v[112:115]
	v_mfma_f32_16x16x32_bf16 v[100:103], v[172:175], v[196:199], v[100:103]
	v_mfma_f32_16x16x32_bf16 v[96:99], v[180:183], v[196:199], v[96:99]
	v_mfma_f32_16x16x32_bf16 v[84:87], v[172:175], v[204:207], v[84:87]
	v_mfma_f32_16x16x32_bf16 v[80:83], v[180:183], v[204:207], v[80:83]
	v_mfma_f32_16x16x32_bf16 v[68:71], v[172:175], v[212:215], v[68:71]
	v_mfma_f32_16x16x32_bf16 v[64:67], v[180:183], v[212:215], v[64:67]
	v_mfma_f32_16x16x32_bf16 v[116:119], v[176:179], v[192:195], v[116:119]
	v_mfma_f32_16x16x32_bf16 v[112:115], v[184:187], v[192:195], v[112:115]
	v_mfma_f32_16x16x32_bf16 v[100:103], v[176:179], v[200:203], v[100:103]
	v_mfma_f32_16x16x32_bf16 v[96:99], v[184:187], v[200:203], v[96:99]
	v_mfma_f32_16x16x32_bf16 v[84:87], v[176:179], v[208:211], v[84:87]
	v_mfma_f32_16x16x32_bf16 v[80:83], v[184:187], v[208:211], v[80:83]
	v_mfma_f32_16x16x32_bf16 v[68:71], v[176:179], v[216:219], v[68:71]
	v_mfma_f32_16x16x32_bf16 v[64:67], v[184:187], v[216:219], v[64:67]
	s_setprio 0
	s_barrier
	s_add_i32 s96, s85, s70
	v_lshl_add_u64 v[220:221], s[64:65], 0, v[138:139]
	s_mov_b32 m0, s96
	ds_read_b128 v[188:191], v168 offset:16384
	ds_read_b128 v[192:195], v168 offset:17408
	ds_read_b128 v[196:199], v168 offset:18432
	ds_read_b128 v[200:203], v168 offset:19456
	ds_read_b128 v[204:207], v168 offset:20480
	ds_read_b128 v[208:211], v168 offset:21504
	ds_read_b128 v[212:215], v168 offset:22528
	ds_read_b128 v[216:219], v168 offset:23552
	global_load_lds_dwordx4 v[220:221], off
	s_add_i32 m0, s96, 0x2000
	s_add_u32 s96, s64, 0x80000
	v_lshl_add_u64 v[222:223], s[64:65], 0, v[142:143]
	s_addc_u32 s97, s65, 0
	s_add_i32 s98, s86, s70
	global_load_lds_dwordx4 v[222:223], off
	v_lshl_add_u64 v[228:229], s[96:97], 0, v[138:139]
	s_mov_b32 m0, s98
	v_lshl_add_u64 v[230:231], s[66:67], 0, v[140:141]
	global_load_lds_dwordx4 v[228:229], off
	v_lshl_add_u64 v[228:229], s[96:97], 0, v[142:143]
	s_add_i32 m0, s98, 0x2000
	s_nop 0
	global_load_lds_dwordx4 v[228:229], off
	v_lshl_add_u64 v[228:229], s[66:67], 0, v[136:137]
	s_mov_b32 m0, s71
	s_nop 0
	global_load_lds_dwordx4 v[228:229], off
	s_mov_b32 m0, s72
	s_nop 0
	global_load_lds_dwordx4 v[230:231], off
	s_cmp_eq_u32 s95, -2
	s_cbranch_scc1 .Ltw0_1
	s_waitcnt vmcnt(8)
.Ltw0_1:
	s_waitcnt lgkmcnt(0)
	s_barrier
	s_setprio 1
	s_waitcnt lgkmcnt(0)
	v_mfma_f32_16x16x32_bf16 v[60:63], v[128:131], v[188:191], v[60:63]
	v_mfma_f32_16x16x32_bf16 v[56:59], v[156:159], v[188:191], v[56:59]
	v_mfma_f32_16x16x32_bf16 v[44:47], v[128:131], v[196:199], v[44:47]
	v_mfma_f32_16x16x32_bf16 v[40:43], v[156:159], v[196:199], v[40:43]
	v_mfma_f32_16x16x32_bf16 v[28:31], v[128:131], v[204:207], v[28:31]
	v_mfma_f32_16x16x32_bf16 v[24:27], v[156:159], v[204:207], v[24:27]
	v_mfma_f32_16x16x32_bf16 v[12:15], v[128:131], v[212:215], v[12:15]
	v_mfma_f32_16x16x32_bf16 v[8:11], v[156:159], v[212:215], v[8:11]
	v_mfma_f32_16x16x32_bf16 v[60:63], v[132:135], v[192:195], v[60:63]
	v_mfma_f32_16x16x32_bf16 v[56:59], v[160:163], v[192:195], v[56:59]
	v_mfma_f32_16x16x32_bf16 v[44:47], v[132:135], v[200:203], v[44:47]
	v_mfma_f32_16x16x32_bf16 v[40:43], v[160:163], v[200:203], v[40:43]
	v_mfma_f32_16x16x32_bf16 v[28:31], v[132:135], v[208:211], v[28:31]
	v_mfma_f32_16x16x32_bf16 v[24:27], v[160:163], v[208:211], v[24:27]
	v_mfma_f32_16x16x32_bf16 v[12:15], v[132:135], v[216:219], v[12:15]
	v_mfma_f32_16x16x32_bf16 v[8:11], v[160:163], v[216:219], v[8:11]
	s_setprio 0
	s_setprio 1
	v_mfma_f32_16x16x32_bf16 v[52:55], v[172:175], v[188:191], v[52:55]
	v_mfma_f32_16x16x32_bf16 v[48:51], v[180:183], v[188:191], v[48:51]
	v_mfma_f32_16x16x32_bf16 v[36:39], v[172:175], v[196:199], v[36:39]
	v_mfma_f32_16x16x32_bf16 v[32:35], v[180:183], v[196:199], v[32:35]
	v_mfma_f32_16x16x32_bf16 v[20:23], v[172:175], v[204:207], v[20:23]
	v_mfma_f32_16x16x32_bf16 v[16:19], v[180:183], v[204:207], v[16:19]
	v_mfma_f32_16x16x32_bf16 v[4:7], v[172:175], v[212:215], v[4:7]
	v_mfma_f32_16x16x32_bf16 v[0:3], v[180:183], v[212:215], v[0:3]
	v_mfma_f32_16x16x32_bf16 v[52:55], v[176:179], v[192:195], v[52:55]
	v_mfma_f32_16x16x32_bf16 v[48:51], v[184:187], v[192:195], v[48:51]
	v_mfma_f32_16x16x32_bf16 v[36:39], v[176:179], v[200:203], v[36:39]
	v_mfma_f32_16x16x32_bf16 v[32:35], v[184:187], v[200:203], v[32:35]
	v_mfma_f32_16x16x32_bf16 v[20:23], v[176:179], v[208:211], v[20:23]
	v_mfma_f32_16x16x32_bf16 v[16:19], v[184:187], v[208:211], v[16:19]
	v_mfma_f32_16x16x32_bf16 v[4:7], v[176:179], v[216:219], v[4:7]
	v_mfma_f32_16x16x32_bf16 v[0:3], v[184:187], v[216:219], v[0:3]
	s_setprio 0
	s_barrier
	s_add_i32 s96, 0, 0x18000
	v_add_u32_e32 v144, s96, v165
	s_add_i32 s97, 0, 0x1c000
	ds_read_b128 v[128:131], v144
	ds_read_b128 v[132:135], v144 offset:1024
	ds_read_b128 v[156:159], v144 offset:2048
	ds_read_b128 v[160:163], v144 offset:3072
	v_add_u32_e32 v144, s97, v165
	ds_read_b128 v[172:175], v144
	ds_read_b128 v[176:179], v144 offset:1024
	ds_read_b128 v[180:183], v144 offset:2048
	ds_read_b128 v[184:187], v144 offset:3072
	s_add_u32 s66, s66, 0x80000
	s_addc_u32 s67, s67, 0
	s_mov_b32 m0, s73
	v_lshl_add_u64 v[232:233], s[66:67], 0, v[136:137]
	ds_read_b128 v[188:191], v168 offset:32768
	ds_read_b128 v[192:195], v168 offset:33792
	ds_read_b128 v[196:199], v168 offset:34816
	ds_read_b128 v[200:203], v168 offset:35840
	ds_read_b128 v[204:207], v168 offset:36864
	ds_read_b128 v[208:211], v168 offset:37888
	ds_read_b128 v[212:215], v168 offset:38912
	ds_read_b128 v[216:219], v168 offset:39936
	global_load_lds_dwordx4 v[232:233], off
	v_lshl_add_u64 v[232:233], s[66:67], 0, v[140:141]
	s_mov_b32 m0, s74
	s_nop 0
	global_load_lds_dwordx4 v[232:233], off
	s_waitcnt vmcnt(8)
	s_waitcnt lgkmcnt(0)
	s_barrier
	s_setprio 1
	s_waitcnt lgkmcnt(0)
	v_mfma_f32_16x16x32_bf16 v[124:127], v[128:131], v[188:191], v[124:127]
	v_mfma_f32_16x16x32_bf16 v[120:123], v[156:159], v[188:191], v[120:123]
	v_mfma_f32_16x16x32_bf16 v[108:111], v[128:131], v[196:199], v[108:111]
	v_mfma_f32_16x16x32_bf16 v[104:107], v[156:159], v[196:199], v[104:107]
	v_mfma_f32_16x16x32_bf16 v[92:95], v[128:131], v[204:207], v[92:95]
	v_mfma_f32_16x16x32_bf16 v[88:91], v[156:159], v[204:207], v[88:91]
	v_mfma_f32_16x16x32_bf16 v[76:79], v[128:131], v[212:215], v[76:79]
	v_mfma_f32_16x16x32_bf16 v[72:75], v[156:159], v[212:215], v[72:75]
	v_mfma_f32_16x16x32_bf16 v[124:127], v[132:135], v[192:195], v[124:127]
	v_mfma_f32_16x16x32_bf16 v[120:123], v[160:163], v[192:195], v[120:123]
	v_mfma_f32_16x16x32_bf16 v[108:111], v[132:135], v[200:203], v[108:111]
	v_mfma_f32_16x16x32_bf16 v[104:107], v[160:163], v[200:203], v[104:107]
	v_mfma_f32_16x16x32_bf16 v[92:95], v[132:135], v[208:211], v[92:95]
	v_mfma_f32_16x16x32_bf16 v[88:91], v[160:163], v[208:211], v[88:91]
	v_mfma_f32_16x16x32_bf16 v[76:79], v[132:135], v[216:219], v[76:79]
	v_mfma_f32_16x16x32_bf16 v[72:75], v[160:163], v[216:219], v[72:75]
	s_setprio 0
	s_setprio 1
	v_mfma_f32_16x16x32_bf16 v[116:119], v[172:175], v[188:191], v[116:119]
	v_mfma_f32_16x16x32_bf16 v[112:115], v[180:183], v[188:191], v[112:115]
	v_mfma_f32_16x16x32_bf16 v[100:103], v[172:175], v[196:199], v[100:103]
	v_mfma_f32_16x16x32_bf16 v[96:99], v[180:183], v[196:199], v[96:99]
	v_mfma_f32_16x16x32_bf16 v[84:87], v[172:175], v[204:207], v[84:87]
	v_mfma_f32_16x16x32_bf16 v[80:83], v[180:183], v[204:207], v[80:83]
	v_mfma_f32_16x16x32_bf16 v[68:71], v[172:175], v[212:215], v[68:71]
	v_mfma_f32_16x16x32_bf16 v[64:67], v[180:183], v[212:215], v[64:67]
	v_mfma_f32_16x16x32_bf16 v[116:119], v[176:179], v[192:195], v[116:119]
	v_mfma_f32_16x16x32_bf16 v[112:115], v[184:187], v[192:195], v[112:115]
	v_mfma_f32_16x16x32_bf16 v[100:103], v[176:179], v[200:203], v[100:103]
	v_mfma_f32_16x16x32_bf16 v[96:99], v[184:187], v[200:203], v[96:99]
	v_mfma_f32_16x16x32_bf16 v[84:87], v[176:179], v[208:211], v[84:87]
	v_mfma_f32_16x16x32_bf16 v[80:83], v[184:187], v[208:211], v[80:83]
	v_mfma_f32_16x16x32_bf16 v[68:71], v[176:179], v[216:219], v[68:71]
	v_mfma_f32_16x16x32_bf16 v[64:67], v[184:187], v[216:219], v[64:67]
	s_setprio 0
	s_barrier
	s_add_i32 s66, s96, s70
	v_lshl_add_u64 v[220:221], v[220:221], 0, s[40:41]
	s_mov_b32 m0, s66
	ds_read_b128 v[188:191], v168 offset:49152
	ds_read_b128 v[192:195], v168 offset:50176
	ds_read_b128 v[196:199], v168 offset:51200
	ds_read_b128 v[200:203], v168 offset:52224
	ds_read_b128 v[204:207], v168 offset:53248
	ds_read_b128 v[208:211], v168 offset:54272
	ds_read_b128 v[212:215], v168 offset:55296
	ds_read_b128 v[216:219], v168 offset:56320
	global_load_lds_dwordx4 v[220:221], off
	s_add_i32 m0, s66, 0x2000
	s_add_u32 s64, s64, 0x80080
	v_lshl_add_u64 v[220:221], v[222:223], 0, s[40:41]
	s_addc_u32 s65, s65, 0
	s_add_i32 s66, s97, s70
	global_load_lds_dwordx4 v[220:221], off
	v_lshl_add_u64 v[220:221], s[64:65], 0, v[138:139]
	s_mov_b32 m0, s66
	s_nop 0
	global_load_lds_dwordx4 v[220:221], off
	v_lshl_add_u64 v[220:221], s[64:65], 0, v[142:143]
	s_add_i32 m0, s66, 0x2000
	s_nop 0
	global_load_lds_dwordx4 v[220:221], off
	v_lshl_add_u64 v[220:221], v[228:229], 0, s[40:41]
	s_mov_b32 m0, s76
	s_nop 0
	global_load_lds_dwordx4 v[220:221], off
	v_lshl_add_u64 v[220:221], v[230:231], 0, s[40:41]
	s_mov_b32 m0, s77
	s_nop 0
	global_load_lds_dwordx4 v[220:221], off
	s_waitcnt vmcnt(8)
	s_waitcnt lgkmcnt(0)
	s_barrier
	s_setprio 1
	s_waitcnt lgkmcnt(0)
	v_mfma_f32_16x16x32_bf16 v[60:63], v[128:131], v[188:191], v[60:63]
	v_mfma_f32_16x16x32_bf16 v[56:59], v[156:159], v[188:191], v[56:59]
	v_mfma_f32_16x16x32_bf16 v[44:47], v[128:131], v[196:199], v[44:47]
	v_mfma_f32_16x16x32_bf16 v[40:43], v[156:159], v[196:199], v[40:43]
	v_mfma_f32_16x16x32_bf16 v[28:31], v[128:131], v[204:207], v[28:31]
	v_mfma_f32_16x16x32_bf16 v[24:27], v[156:159], v[204:207], v[24:27]
	v_mfma_f32_16x16x32_bf16 v[12:15], v[128:131], v[212:215], v[12:15]
	v_mfma_f32_16x16x32_bf16 v[8:11], v[156:159], v[212:215], v[8:11]
	v_mfma_f32_16x16x32_bf16 v[60:63], v[132:135], v[192:195], v[60:63]
	v_mfma_f32_16x16x32_bf16 v[56:59], v[160:163], v[192:195], v[56:59]
	v_mfma_f32_16x16x32_bf16 v[44:47], v[132:135], v[200:203], v[44:47]
	v_mfma_f32_16x16x32_bf16 v[40:43], v[160:163], v[200:203], v[40:43]
	v_mfma_f32_16x16x32_bf16 v[28:31], v[132:135], v[208:211], v[28:31]
	v_mfma_f32_16x16x32_bf16 v[24:27], v[160:163], v[208:211], v[24:27]
	v_mfma_f32_16x16x32_bf16 v[12:15], v[132:135], v[216:219], v[12:15]
	v_mfma_f32_16x16x32_bf16 v[8:11], v[160:163], v[216:219], v[8:11]
	s_setprio 0
	s_setprio 1
	v_mfma_f32_16x16x32_bf16 v[52:55], v[172:175], v[188:191], v[52:55]
	v_mfma_f32_16x16x32_bf16 v[48:51], v[180:183], v[188:191], v[48:51]
	v_mfma_f32_16x16x32_bf16 v[36:39], v[172:175], v[196:199], v[36:39]
	v_mfma_f32_16x16x32_bf16 v[32:35], v[180:183], v[196:199], v[32:35]
	v_mfma_f32_16x16x32_bf16 v[20:23], v[172:175], v[204:207], v[20:23]
	v_mfma_f32_16x16x32_bf16 v[16:19], v[180:183], v[204:207], v[16:19]
	v_mfma_f32_16x16x32_bf16 v[4:7], v[172:175], v[212:215], v[4:7]
	v_mfma_f32_16x16x32_bf16 v[0:3], v[180:183], v[212:215], v[0:3]
	v_mfma_f32_16x16x32_bf16 v[52:55], v[176:179], v[192:195], v[52:55]
	v_mfma_f32_16x16x32_bf16 v[48:51], v[184:187], v[192:195], v[48:51]
	v_mfma_f32_16x16x32_bf16 v[36:39], v[176:179], v[200:203], v[36:39]
	v_mfma_f32_16x16x32_bf16 v[32:35], v[184:187], v[200:203], v[32:35]
	v_mfma_f32_16x16x32_bf16 v[20:23], v[176:179], v[208:211], v[20:23]
	v_mfma_f32_16x16x32_bf16 v[16:19], v[184:187], v[208:211], v[16:19]
	v_mfma_f32_16x16x32_bf16 v[4:7], v[176:179], v[216:219], v[4:7]
	v_mfma_f32_16x16x32_bf16 v[0:3], v[184:187], v[216:219], v[0:3]
	s_setprio 0
	s_barrier
	s_add_i32 s95, s95, 2
	s_add_u32 s62, s62, 0x100
	s_addc_u32 s63, s63, 0
	s_add_u32 s69, s69, 0x100
	s_addc_u32 s94, s94, 0
	s_cmp_gt_u32 s95, 29
	s_cbranch_scc0 .LBB0_265
	s_and_b64 vcc, exec, s[42:43]
	s_cbranch_vccz .LBB0_268
	s_barrier

.LBB0_468:
	v_mov_b32_e32 v8, v156
	v_mov_b32_e32 v9, v156
	v_pk_mul_f32 v[4:5], v[156:157], v[4:5]
	v_pk_mul_f32 v[6:7], v[8:9], v[6:7]
	v_pk_mul_f32 v[8:9], v[8:9], v[2:3]
	v_pk_mul_f32 v[2:3], v[156:157], v[0:1]
	v_cvt_pk_bf16_f32 v0, v4, v5
	v_lshl_add_u64 v[4:5], v[24:25], 0, s[16:17]
	s_andn2_b64 vcc, exec, s[4:5]
	s_mov_b64 s[4:5], -1
	v_cvt_pk_bf16_f32 v1, v6, v7
	v_cvt_pk_bf16_f32 v2, v2, v3
	v_cvt_pk_bf16_f32 v3, v8, v9
	global_store_dwordx4 v[4:5], v[0:3], off
	s_waitcnt vmcnt(0)

.LBB0_488:
	s_ashr_i32 s45, s44, 31
	s_lshl_b64 s[46:47], s[44:45], 20
	s_add_u32 s46, s61, s46
	s_addc_u32 s47, s62, s47
	s_and_b64 s[48:49], s[4:5], exec
	s_cselect_b32 s45, s47, s55
	s_cselect_b32 s51, s46, s54
	s_ashr_i32 s43, s42, 31
	s_lshl_b64 s[48:49], s[42:43], 20
	s_add_u32 s48, s10, s48
	s_addc_u32 s49, s11, s49
	s_and_b64 s[58:59], s[4:5], exec
	s_cselect_b32 s43, s49, s57
	s_cselect_b32 s83, s48, s56
	s_add_u32 s54, s54, 0x80080
	s_addc_u32 s55, s55, 0
	s_add_u32 s84, s56, 0x100
	v_mov_b32_e32 v0, 0
	s_addc_u32 s85, s57, 0
	s_mov_b32 s86, -2
	v_mov_b32_e32 v1, v0
	v_mov_b32_e32 v2, v0
	v_mov_b32_e32 v3, v0
	v_mov_b32_e32 v4, v0
	v_mov_b32_e32 v5, v0
	v_mov_b32_e32 v6, v0
	v_mov_b32_e32 v7, v0
	v_mov_b32_e32 v8, v0
	v_mov_b32_e32 v9, v0
	v_mov_b32_e32 v10, v0
	v_mov_b32_e32 v11, v0
	v_mov_b32_e32 v16, v0
	v_mov_b32_e32 v17, v0
	v_mov_b32_e32 v18, v0
	v_mov_b32_e32 v19, v0
	v_mov_b32_e32 v24, v0
	v_mov_b32_e32 v25, v0
	v_mov_b32_e32 v26, v0
	v_mov_b32_e32 v27, v0
	v_mov_b32_e32 v32, v0
	v_mov_b32_e32 v33, v0
	v_mov_b32_e32 v34, v0
	v_mov_b32_e32 v35, v0
	v_mov_b32_e32 v40, v0
	v_mov_b32_e32 v41, v0
	v_mov_b32_e32 v42, v0
	v_mov_b32_e32 v43, v0
	v_mov_b32_e32 v48, v0
	v_mov_b32_e32 v49, v0
	v_mov_b32_e32 v50, v0
	v_mov_b32_e32 v51, v0
	v_mov_b32_e32 v12, v0
	v_mov_b32_e32 v13, v0
	v_mov_b32_e32 v14, v0
	v_mov_b32_e32 v15, v0
	v_mov_b32_e32 v20, v0
	v_mov_b32_e32 v21, v0
	v_mov_b32_e32 v22, v0
	v_mov_b32_e32 v23, v0
	v_mov_b32_e32 v28, v0
	v_mov_b32_e32 v29, v0
	v_mov_b32_e32 v30, v0
	v_mov_b32_e32 v31, v0
	v_mov_b32_e32 v36, v0
	v_mov_b32_e32 v37, v0
	v_mov_b32_e32 v38, v0
	v_mov_b32_e32 v39, v0
	v_mov_b32_e32 v44, v0
	v_mov_b32_e32 v45, v0
	v_mov_b32_e32 v46, v0
	v_mov_b32_e32 v47, v0
	v_mov_b32_e32 v52, v0
	v_mov_b32_e32 v53, v0
	v_mov_b32_e32 v54, v0
	v_mov_b32_e32 v55, v0
	v_mov_b32_e32 v56, v0
	v_mov_b32_e32 v57, v0
	v_mov_b32_e32 v58, v0
	v_mov_b32_e32 v59, v0
	v_mov_b32_e32 v60, v0
	v_mov_b32_e32 v61, v0
	v_mov_b32_e32 v62, v0
	v_mov_b32_e32 v63, v0
	v_mov_b32_e32 v64, v0
	v_mov_b32_e32 v65, v0
	v_mov_b32_e32 v66, v0
	v_mov_b32_e32 v67, v0
	v_mov_b32_e32 v68, v0
	v_mov_b32_e32 v69, v0
	v_mov_b32_e32 v70, v0
	v_mov_b32_e32 v71, v0
	v_mov_b32_e32 v72, v0
	v_mov_b32_e32 v73, v0
	v_mov_b32_e32 v74, v0
	v_mov_b32_e32 v75, v0
	v_mov_b32_e32 v80, v0
	v_mov_b32_e32 v81, v0
	v_mov_b32_e32 v82, v0
	v_mov_b32_e32 v83, v0
	v_mov_b32_e32 v88, v0
	v_mov_b32_e32 v89, v0
	v_mov_b32_e32 v90, v0
	v_mov_b32_e32 v91, v0
	v_mov_b32_e32 v96, v0
	v_mov_b32_e32 v97, v0
	v_mov_b32_e32 v98, v0
	v_mov_b32_e32 v99, v0
	v_mov_b32_e32 v104, v0
	v_mov_b32_e32 v105, v0
	v_mov_b32_e32 v106, v0
	v_mov_b32_e32 v107, v0
	v_mov_b32_e32 v112, v0
	v_mov_b32_e32 v113, v0
	v_mov_b32_e32 v114, v0
	v_mov_b32_e32 v115, v0
	v_mov_b32_e32 v76, v0
	v_mov_b32_e32 v77, v0
	v_mov_b32_e32 v78, v0
	v_mov_b32_e32 v79, v0
	v_mov_b32_e32 v84, v0
	v_mov_b32_e32 v85, v0
	v_mov_b32_e32 v86, v0
	v_mov_b32_e32 v87, v0
	v_mov_b32_e32 v92, v0
	v_mov_b32_e32 v93, v0
	v_mov_b32_e32 v94, v0
	v_mov_b32_e32 v95, v0
	v_mov_b32_e32 v100, v0
	v_mov_b32_e32 v101, v0
	v_mov_b32_e32 v102, v0
	v_mov_b32_e32 v103, v0
	v_mov_b32_e32 v108, v0
	v_mov_b32_e32 v109, v0
	v_mov_b32_e32 v110, v0
	v_mov_b32_e32 v111, v0
	v_mov_b32_e32 v116, v0
	v_mov_b32_e32 v117, v0
	v_mov_b32_e32 v118, v0
	v_mov_b32_e32 v119, v0
	v_mov_b32_e32 v120, v0
	v_mov_b32_e32 v121, v0
	v_mov_b32_e32 v122, v0
	v_mov_b32_e32 v123, v0
	v_mov_b32_e32 v124, v0
	v_mov_b32_e32 v125, v0
	v_mov_b32_e32 v126, v0
	v_mov_b32_e32 v127, v0
	s_nop 0
	s_nop 0
.LBB0_489:
	ds_read_b128 v[160:163], v157
	ds_read_b128 v[164:167], v157 offset:1024
	ds_read_b128 v[168:171], v157 offset:2048
	ds_read_b128 v[172:175], v157 offset:3072
	ds_read_b128 v[176:179], v158
	ds_read_b128 v[180:183], v158 offset:1024
	ds_read_b128 v[184:187], v158 offset:2048
	ds_read_b128 v[188:191], v158 offset:3072
	s_add_u32 s56, s54, 0xfff80080
	s_addc_u32 s57, s55, -1
	s_cmp_eq_u32 s86, 28
	s_cselect_b32 s59, s45, s57
	s_cselect_b32 s58, s51, s56
	s_cselect_b32 s57, s43, s85
	s_cselect_b32 s56, s83, s84
	v_lshl_add_u64 v[228:229], s[54:55], 0, v[138:139]
	s_add_i32 m0, s64, 0xc000
	ds_read_b128 v[192:195], v159
	ds_read_b128 v[196:199], v159 offset:1024
	ds_read_b128 v[200:203], v159 offset:2048
	ds_read_b128 v[204:207], v159 offset:3072
	ds_read_b128 v[208:211], v159 offset:4096
	ds_read_b128 v[212:215], v159 offset:5120
	ds_read_b128 v[216:219], v159 offset:6144
	ds_read_b128 v[220:223], v159 offset:7168
	global_load_lds_dwordx4 v[228:229], off
	v_lshl_add_u64 v[228:229], s[54:55], 0, v[140:141]
	s_add_i32 m0, s64, 0xe000
	s_nop 0
	global_load_lds_dwordx4 v[228:229], off
	s_waitcnt vmcnt(8)
	s_waitcnt lgkmcnt(0)
	s_barrier
	s_setprio 1
	s_waitcnt lgkmcnt(0)
	v_mfma_f32_16x16x32_bf16 v[124:127], v[160:163], v[192:195], v[124:127]
	v_mfma_f32_16x16x32_bf16 v[120:123], v[168:171], v[192:195], v[120:123]
	v_mfma_f32_16x16x32_bf16 v[116:119], v[160:163], v[200:203], v[116:119]
	v_mfma_f32_16x16x32_bf16 v[108:111], v[168:171], v[200:203], v[108:111]
	v_mfma_f32_16x16x32_bf16 v[100:103], v[160:163], v[208:211], v[100:103]
	v_mfma_f32_16x16x32_bf16 v[92:95], v[168:171], v[208:211], v[92:95]
	v_mfma_f32_16x16x32_bf16 v[84:87], v[160:163], v[216:219], v[84:87]
	v_mfma_f32_16x16x32_bf16 v[76:79], v[168:171], v[216:219], v[76:79]
	v_mfma_f32_16x16x32_bf16 v[124:127], v[164:167], v[196:199], v[124:127]
	v_mfma_f32_16x16x32_bf16 v[120:123], v[172:175], v[196:199], v[120:123]
	v_mfma_f32_16x16x32_bf16 v[116:119], v[164:167], v[204:207], v[116:119]
	v_mfma_f32_16x16x32_bf16 v[108:111], v[172:175], v[204:207], v[108:111]
	v_mfma_f32_16x16x32_bf16 v[100:103], v[164:167], v[212:215], v[100:103]
	v_mfma_f32_16x16x32_bf16 v[92:95], v[172:175], v[212:215], v[92:95]
	v_mfma_f32_16x16x32_bf16 v[84:87], v[164:167], v[220:223], v[84:87]
	v_mfma_f32_16x16x32_bf16 v[76:79], v[172:175], v[220:223], v[76:79]
	s_setprio 0
	s_setprio 1
	v_mfma_f32_16x16x32_bf16 v[112:115], v[176:179], v[192:195], v[112:115]
	v_mfma_f32_16x16x32_bf16 v[104:107], v[184:187], v[192:195], v[104:107]
	v_mfma_f32_16x16x32_bf16 v[96:99], v[176:179], v[200:203], v[96:99]
	v_mfma_f32_16x16x32_bf16 v[88:91], v[184:187], v[200:203], v[88:91]
	v_mfma_f32_16x16x32_bf16 v[80:83], v[176:179], v[208:211], v[80:83]
	v_mfma_f32_16x16x32_bf16 v[72:75], v[184:187], v[208:211], v[72:75]
	v_mfma_f32_16x16x32_bf16 v[68:71], v[176:179], v[216:219], v[68:71]
	v_mfma_f32_16x16x32_bf16 v[64:67], v[184:187], v[216:219], v[64:67]
	v_mfma_f32_16x16x32_bf16 v[112:115], v[180:183], v[196:199], v[112:115]
	v_mfma_f32_16x16x32_bf16 v[104:107], v[188:191], v[196:199], v[104:107]
	v_mfma_f32_16x16x32_bf16 v[96:99], v[180:183], v[204:207], v[96:99]
	v_mfma_f32_16x16x32_bf16 v[88:91], v[188:191], v[204:207], v[88:91]
	v_mfma_f32_16x16x32_bf16 v[80:83], v[180:183], v[212:215], v[80:83]
	v_mfma_f32_16x16x32_bf16 v[72:75], v[188:191], v[212:215], v[72:75]
	v_mfma_f32_16x16x32_bf16 v[68:71], v[180:183], v[220:223], v[68:71]
	v_mfma_f32_16x16x32_bf16 v[64:67], v[188:191], v[220:223], v[64:67]
	s_setprio 0
	s_barrier
	s_add_i32 s87, s75, s63
	v_lshl_add_u64 v[228:229], s[56:57], 0, v[130:131]
	s_mov_b32 m0, s87
	ds_read_b128 v[192:195], v159 offset:16384
	ds_read_b128 v[196:199], v159 offset:17408
	ds_read_b128 v[200:203], v159 offset:18432
	ds_read_b128 v[204:207], v159 offset:19456
	ds_read_b128 v[208:211], v159 offset:20480
	ds_read_b128 v[212:215], v159 offset:21504
	ds_read_b128 v[216:219], v159 offset:22528
	ds_read_b128 v[220:223], v159 offset:23552
	global_load_lds_dwordx4 v[228:229], off
	s_add_i32 m0, s87, 0x2000
	s_add_u32 s88, s56, 0x80000
	v_lshl_add_u64 v[230:231], s[56:57], 0, v[134:135]
	s_addc_u32 s89, s57, 0
	s_add_i32 s87, s76, s63
	global_load_lds_dwordx4 v[230:231], off
	v_lshl_add_u64 v[232:233], s[88:89], 0, v[130:131]
	s_mov_b32 m0, s87
	v_lshl_add_u64 v[234:235], s[58:59], 0, v[132:133]
	global_load_lds_dwordx4 v[232:233], off
	v_lshl_add_u64 v[232:233], s[88:89], 0, v[134:135]
	s_add_i32 m0, s87, 0x2000
	s_nop 0
	global_load_lds_dwordx4 v[232:233], off
	v_lshl_add_u64 v[232:233], s[58:59], 0, v[128:129]
	s_mov_b32 m0, s64
	s_nop 0
	global_load_lds_dwordx4 v[232:233], off
	s_mov_b32 m0, s65
	s_nop 0
	global_load_lds_dwordx4 v[234:235], off
	s_waitcnt vmcnt(8)
	s_waitcnt lgkmcnt(0)
	s_barrier
	s_setprio 1
	s_waitcnt lgkmcnt(0)
	v_mfma_f32_16x16x32_bf16 v[60:63], v[160:163], v[192:195], v[60:63]
	v_mfma_f32_16x16x32_bf16 v[56:59], v[168:171], v[192:195], v[56:59]
	v_mfma_f32_16x16x32_bf16 v[52:55], v[160:163], v[200:203], v[52:55]
	v_mfma_f32_16x16x32_bf16 v[44:47], v[168:171], v[200:203], v[44:47]
	v_mfma_f32_16x16x32_bf16 v[36:39], v[160:163], v[208:211], v[36:39]
	v_mfma_f32_16x16x32_bf16 v[28:31], v[168:171], v[208:211], v[28:31]
	v_mfma_f32_16x16x32_bf16 v[20:23], v[160:163], v[216:219], v[20:23]
	v_mfma_f32_16x16x32_bf16 v[12:15], v[168:171], v[216:219], v[12:15]
	v_mfma_f32_16x16x32_bf16 v[60:63], v[164:167], v[196:199], v[60:63]
	v_mfma_f32_16x16x32_bf16 v[56:59], v[172:175], v[196:199], v[56:59]
	v_mfma_f32_16x16x32_bf16 v[52:55], v[164:167], v[204:207], v[52:55]
	v_mfma_f32_16x16x32_bf16 v[44:47], v[172:175], v[204:207], v[44:47]
	v_mfma_f32_16x16x32_bf16 v[36:39], v[164:167], v[212:215], v[36:39]
	v_mfma_f32_16x16x32_bf16 v[28:31], v[172:175], v[212:215], v[28:31]
	v_mfma_f32_16x16x32_bf16 v[20:23], v[164:167], v[220:223], v[20:23]
	v_mfma_f32_16x16x32_bf16 v[12:15], v[172:175], v[220:223], v[12:15]
	s_setprio 0
	s_setprio 1
	v_mfma_f32_16x16x32_bf16 v[48:51], v[176:179], v[192:195], v[48:51]
	v_mfma_f32_16x16x32_bf16 v[40:43], v[184:187], v[192:195], v[40:43]
	v_mfma_f32_16x16x32_bf16 v[32:35], v[176:179], v[200:203], v[32:35]
	v_mfma_f32_16x16x32_bf16 v[24:27], v[184:187], v[200:203], v[24:27]
	v_mfma_f32_16x16x32_bf16 v[16:19], v[176:179], v[208:211], v[16:19]
	v_mfma_f32_16x16x32_bf16 v[8:11], v[184:187], v[208:211], v[8:11]
	v_mfma_f32_16x16x32_bf16 v[4:7], v[176:179], v[216:219], v[4:7]
	v_mfma_f32_16x16x32_bf16 v[0:3], v[184:187], v[216:219], v[0:3]
	v_mfma_f32_16x16x32_bf16 v[48:51], v[180:183], v[196:199], v[48:51]
	v_mfma_f32_16x16x32_bf16 v[40:43], v[188:191], v[196:199], v[40:43]
	v_mfma_f32_16x16x32_bf16 v[32:35], v[180:183], v[204:207], v[32:35]
	v_mfma_f32_16x16x32_bf16 v[24:27], v[188:191], v[204:207], v[24:27]
	v_mfma_f32_16x16x32_bf16 v[16:19], v[180:183], v[212:215], v[16:19]
	v_mfma_f32_16x16x32_bf16 v[8:11], v[188:191], v[212:215], v[8:11]
	v_mfma_f32_16x16x32_bf16 v[4:7], v[180:183], v[220:223], v[4:7]
	v_mfma_f32_16x16x32_bf16 v[0:3], v[188:191], v[220:223], v[0:3]
	s_setprio 0
	s_barrier
	s_add_i32 s87, 0, 0x18000
	v_add_u32_e32 v147, s87, v156
	s_add_i32 s88, 0, 0x1c000
	ds_read_b128 v[160:163], v147
	ds_read_b128 v[164:167], v147 offset:1024
	ds_read_b128 v[168:171], v147 offset:2048
	ds_read_b128 v[172:175], v147 offset:3072
	v_add_u32_e32 v147, s88, v156
	ds_read_b128 v[176:179], v147
	ds_read_b128 v[180:183], v147 offset:1024
	ds_read_b128 v[184:187], v147 offset:2048
	ds_read_b128 v[188:191], v147 offset:3072
	s_add_u32 s58, s58, 0x80000
	s_addc_u32 s59, s59, 0
	s_mov_b32 m0, s66
	v_lshl_add_u64 v[236:237], s[58:59], 0, v[128:129]
	ds_read_b128 v[192:195], v159 offset:32768
	ds_read_b128 v[196:199], v159 offset:33792
	ds_read_b128 v[200:203], v159 offset:34816
	ds_read_b128 v[204:207], v159 offset:35840
	ds_read_b128 v[208:211], v159 offset:36864
	ds_read_b128 v[212:215], v159 offset:37888
	ds_read_b128 v[216:219], v159 offset:38912
	ds_read_b128 v[220:223], v159 offset:39936
	global_load_lds_dwordx4 v[236:237], off
	v_lshl_add_u64 v[236:237], s[58:59], 0, v[132:133]
	s_mov_b32 m0, s67
	s_nop 0
	global_load_lds_dwordx4 v[236:237], off
	s_waitcnt vmcnt(8)
	s_waitcnt lgkmcnt(0)
	s_barrier
	s_setprio 1
	s_waitcnt lgkmcnt(0)
	v_mfma_f32_16x16x32_bf16 v[124:127], v[160:163], v[192:195], v[124:127]
	v_mfma_f32_16x16x32_bf16 v[120:123], v[168:171], v[192:195], v[120:123]
	v_mfma_f32_16x16x32_bf16 v[116:119], v[160:163], v[200:203], v[116:119]
	v_mfma_f32_16x16x32_bf16 v[108:111], v[168:171], v[200:203], v[108:111]
	v_mfma_f32_16x16x32_bf16 v[100:103], v[160:163], v[208:211], v[100:103]
	v_mfma_f32_16x16x32_bf16 v[92:95], v[168:171], v[208:211], v[92:95]
	v_mfma_f32_16x16x32_bf16 v[84:87], v[160:163], v[216:219], v[84:87]
	v_mfma_f32_16x16x32_bf16 v[76:79], v[168:171], v[216:219], v[76:79]
	v_mfma_f32_16x16x32_bf16 v[124:127], v[164:167], v[196:199], v[124:127]
	v_mfma_f32_16x16x32_bf16 v[120:123], v[172:175], v[196:199], v[120:123]
	v_mfma_f32_16x16x32_bf16 v[116:119], v[164:167], v[204:207], v[116:119]
	v_mfma_f32_16x16x32_bf16 v[108:111], v[172:175], v[204:207], v[108:111]
	v_mfma_f32_16x16x32_bf16 v[100:103], v[164:167], v[212:215], v[100:103]
	v_mfma_f32_16x16x32_bf16 v[92:95], v[172:175], v[212:215], v[92:95]
	v_mfma_f32_16x16x32_bf16 v[84:87], v[164:167], v[220:223], v[84:87]
	v_mfma_f32_16x16x32_bf16 v[76:79], v[172:175], v[220:223], v[76:79]
	s_setprio 0
	s_setprio 1
	v_mfma_f32_16x16x32_bf16 v[112:115], v[176:179], v[192:195], v[112:115]
	v_mfma_f32_16x16x32_bf16 v[104:107], v[184:187], v[192:195], v[104:107]
	v_mfma_f32_16x16x32_bf16 v[96:99], v[176:179], v[200:203], v[96:99]
	v_mfma_f32_16x16x32_bf16 v[88:91], v[184:187], v[200:203], v[88:91]
	v_mfma_f32_16x16x32_bf16 v[80:83], v[176:179], v[208:211], v[80:83]
	v_mfma_f32_16x16x32_bf16 v[72:75], v[184:187], v[208:211], v[72:75]
	v_mfma_f32_16x16x32_bf16 v[68:71], v[176:179], v[216:219], v[68:71]
	v_mfma_f32_16x16x32_bf16 v[64:67], v[184:187], v[216:219], v[64:67]
	v_mfma_f32_16x16x32_bf16 v[112:115], v[180:183], v[196:199], v[112:115]
	v_mfma_f32_16x16x32_bf16 v[104:107], v[188:191], v[196:199], v[104:107]
	v_mfma_f32_16x16x32_bf16 v[96:99], v[180:183], v[204:207], v[96:99]
	v_mfma_f32_16x16x32_bf16 v[88:91], v[188:191], v[204:207], v[88:91]
	v_mfma_f32_16x16x32_bf16 v[80:83], v[180:183], v[212:215], v[80:83]
	v_mfma_f32_16x16x32_bf16 v[72:75], v[188:191], v[212:215], v[72:75]
	v_mfma_f32_16x16x32_bf16 v[68:71], v[180:183], v[220:223], v[68:71]
	v_mfma_f32_16x16x32_bf16 v[64:67], v[188:191], v[220:223], v[64:67]
	s_setprio 0
	s_barrier
	s_add_i32 s58, s87, s63
	v_lshl_add_u64 v[228:229], v[228:229], 0, s[38:39]
	s_mov_b32 m0, s58
	ds_read_b128 v[192:195], v159 offset:49152
	ds_read_b128 v[196:199], v159 offset:50176
	ds_read_b128 v[200:203], v159 offset:51200
	ds_read_b128 v[204:207], v159 offset:52224
	ds_read_b128 v[208:211], v159 offset:53248
	ds_read_b128 v[212:215], v159 offset:54272
	ds_read_b128 v[216:219], v159 offset:55296
	ds_read_b128 v[220:223], v159 offset:56320
	global_load_lds_dwordx4 v[228:229], off
	s_add_i32 m0, s58, 0x2000
	s_add_u32 s56, s56, 0x80080
	v_lshl_add_u64 v[228:229], v[230:231], 0, s[38:39]
	s_addc_u32 s57, s57, 0
	s_add_i32 s58, s88, s63
	global_load_lds_dwordx4 v[228:229], off
	v_lshl_add_u64 v[228:229], s[56:57], 0, v[130:131]
	s_mov_b32 m0, s58
	s_nop 0
	global_load_lds_dwordx4 v[228:229], off
	v_lshl_add_u64 v[228:229], s[56:57], 0, v[134:135]
	s_add_i32 m0, s58, 0x2000
	s_nop 0
	global_load_lds_dwordx4 v[228:229], off
	v_lshl_add_u64 v[228:229], v[232:233], 0, s[38:39]
	s_mov_b32 m0, s71
	s_nop 0
	global_load_lds_dwordx4 v[228:229], off
	v_lshl_add_u64 v[228:229], v[234:235], 0, s[38:39]
	s_mov_b32 m0, s72
	s_nop 0
	global_load_lds_dwordx4 v[228:229], off
	s_waitcnt vmcnt(8)
	s_waitcnt lgkmcnt(0)
	s_barrier
	s_setprio 1
	s_waitcnt lgkmcnt(0)
	v_mfma_f32_16x16x32_bf16 v[60:63], v[160:163], v[192:195], v[60:63]
	v_mfma_f32_16x16x32_bf16 v[56:59], v[168:171], v[192:195], v[56:59]
	v_mfma_f32_16x16x32_bf16 v[52:55], v[160:163], v[200:203], v[52:55]
	v_mfma_f32_16x16x32_bf16 v[44:47], v[168:171], v[200:203], v[44:47]
	v_mfma_f32_16x16x32_bf16 v[36:39], v[160:163], v[208:211], v[36:39]
	v_mfma_f32_16x16x32_bf16 v[28:31], v[168:171], v[208:211], v[28:31]
	v_mfma_f32_16x16x32_bf16 v[20:23], v[160:163], v[216:219], v[20:23]
	v_mfma_f32_16x16x32_bf16 v[12:15], v[168:171], v[216:219], v[12:15]
	v_mfma_f32_16x16x32_bf16 v[60:63], v[164:167], v[196:199], v[60:63]
	v_mfma_f32_16x16x32_bf16 v[56:59], v[172:175], v[196:199], v[56:59]
	v_mfma_f32_16x16x32_bf16 v[52:55], v[164:167], v[204:207], v[52:55]
	v_mfma_f32_16x16x32_bf16 v[44:47], v[172:175], v[204:207], v[44:47]
	v_mfma_f32_16x16x32_bf16 v[36:39], v[164:167], v[212:215], v[36:39]
	v_mfma_f32_16x16x32_bf16 v[28:31], v[172:175], v[212:215], v[28:31]
	v_mfma_f32_16x16x32_bf16 v[20:23], v[164:167], v[220:223], v[20:23]
	v_mfma_f32_16x16x32_bf16 v[12:15], v[172:175], v[220:223], v[12:15]
	s_setprio 0
	s_setprio 1
	v_mfma_f32_16x16x32_bf16 v[48:51], v[176:179], v[192:195], v[48:51]
	v_mfma_f32_16x16x32_bf16 v[40:43], v[184:187], v[192:195], v[40:43]
	v_mfma_f32_16x16x32_bf16 v[32:35], v[176:179], v[200:203], v[32:35]
	v_mfma_f32_16x16x32_bf16 v[24:27], v[184:187], v[200:203], v[24:27]
	v_mfma_f32_16x16x32_bf16 v[16:19], v[176:179], v[208:211], v[16:19]
	v_mfma_f32_16x16x32_bf16 v[8:11], v[184:187], v[208:211], v[8:11]
	v_mfma_f32_16x16x32_bf16 v[4:7], v[176:179], v[216:219], v[4:7]
	v_mfma_f32_16x16x32_bf16 v[0:3], v[184:187], v[216:219], v[0:3]
	v_mfma_f32_16x16x32_bf16 v[48:51], v[180:183], v[196:199], v[48:51]
	v_mfma_f32_16x16x32_bf16 v[40:43], v[188:191], v[196:199], v[40:43]
	v_mfma_f32_16x16x32_bf16 v[32:35], v[180:183], v[204:207], v[32:35]
	v_mfma_f32_16x16x32_bf16 v[24:27], v[188:191], v[204:207], v[24:27]
	v_mfma_f32_16x16x32_bf16 v[16:19], v[180:183], v[212:215], v[16:19]
	v_mfma_f32_16x16x32_bf16 v[8:11], v[188:191], v[212:215], v[8:11]
	v_mfma_f32_16x16x32_bf16 v[4:7], v[180:183], v[220:223], v[4:7]
	v_mfma_f32_16x16x32_bf16 v[0:3], v[188:191], v[220:223], v[0:3]
	s_setprio 0
	s_barrier
	s_add_i32 s86, s86, 2
	s_add_u32 s54, s54, 0x100
	s_addc_u32 s55, s55, 0
	s_add_u32 s84, s84, 0x100
	s_addc_u32 s85, s85, 0
	s_cmp_gt_u32 s86, 29
	s_cbranch_scc0 .LBB0_489
	s_and_b64 vcc, exec, s[40:41]
	s_cbranch_vccz .LBB0_492
	s_barrier
